# adds: P0 adaLN silu staging loop issues its 36 loads together instead of 36 dependent load-wait rounds
# speedup vs baseline: 1.0050x; 1.0050x over previous
; __device__ __forceinline__ void adaln_unit(const Args& a, LAS unsigned char* lds, int unit, int tid, int wave, int lane) {
;     ...
;     for (int kh = 0; kh < 2; ++kh) {
;         __syncthreads();
;         for (int i = tid; i < 18 * 1024; i += NTHR) { const int r = i >> 10, k = (i & 1023) + kh * 1024; const float c = r < 2 ? a.in[I_CP][r * 2048 + k] : a.in[I_CS][(r - 2) * 2048 + k];
;             sc[i] = c / (1.0f + __expf(-c)); }
;         __syncthreads();
.LBB0_12:
	s_barrier
	s_and_saveexec_b64 s[80:81], s[6:7]
	s_cbranch_execz .LBB0_19
	v_add_u32_e32 v200, s58, v41
	v_lshlrev_b32_e32 v200, 2, v200
	v_add_u32_e32 v201, 0x800, v200
	v_add_u32_e32 v202, 0x10000, v149
	s_add_u32 s84, s44, 0x0
	s_addc_u32 s85, s45, 0
	s_nop 1
	global_load_dword v162, v200, s[84:85]
	global_load_dword v163, v201, s[84:85]
	s_add_u32 s84, s44, 0x2000
	s_addc_u32 s85, s45, 0
	s_nop 1
	global_load_dword v164, v200, s[84:85]
	global_load_dword v165, v201, s[84:85]
	s_add_u32 s84, s46, 0x0
	s_addc_u32 s85, s47, 0
	s_nop 1
	global_load_dword v166, v200, s[84:85]
	global_load_dword v167, v201, s[84:85]
	s_add_u32 s84, s46, 0x2000
	s_addc_u32 s85, s47, 0
	s_nop 1
	global_load_dword v168, v200, s[84:85]
	global_load_dword v169, v201, s[84:85]
	s_add_u32 s84, s46, 0x4000
	s_addc_u32 s85, s47, 0
	s_nop 1
	global_load_dword v170, v200, s[84:85]
	global_load_dword v171, v201, s[84:85]
	s_add_u32 s84, s46, 0x6000
	s_addc_u32 s85, s47, 0
	s_nop 1
	global_load_dword v172, v200, s[84:85]
	global_load_dword v173, v201, s[84:85]
	s_add_u32 s84, s46, 0x8000
	s_addc_u32 s85, s47, 0
	s_nop 1
	global_load_dword v174, v200, s[84:85]
	global_load_dword v175, v201, s[84:85]
	s_add_u32 s84, s46, 0xa000
	s_addc_u32 s85, s47, 0
	s_nop 1
	global_load_dword v176, v200, s[84:85]
	global_load_dword v177, v201, s[84:85]
	s_add_u32 s84, s46, 0xc000
	s_addc_u32 s85, s47, 0
	s_nop 1
	global_load_dword v178, v200, s[84:85]
	global_load_dword v179, v201, s[84:85]
	s_add_u32 s84, s46, 0xe000
	s_addc_u32 s85, s47, 0
	s_nop 1
	global_load_dword v180, v200, s[84:85]
	global_load_dword v181, v201, s[84:85]
	s_add_u32 s84, s46, 0x10000
	s_addc_u32 s85, s47, 0
	s_nop 1
	global_load_dword v182, v200, s[84:85]
	global_load_dword v183, v201, s[84:85]
	s_add_u32 s84, s46, 0x12000
	s_addc_u32 s85, s47, 0
	s_nop 1
	global_load_dword v184, v200, s[84:85]
	global_load_dword v185, v201, s[84:85]
	s_add_u32 s84, s46, 0x14000
	s_addc_u32 s85, s47, 0
	s_nop 1
	global_load_dword v186, v200, s[84:85]
	global_load_dword v187, v201, s[84:85]
	s_add_u32 s84, s46, 0x16000
	s_addc_u32 s85, s47, 0
	s_nop 1
	global_load_dword v188, v200, s[84:85]
	global_load_dword v189, v201, s[84:85]
	s_add_u32 s84, s46, 0x18000
	s_addc_u32 s85, s47, 0
	s_nop 1
	global_load_dword v190, v200, s[84:85]
	global_load_dword v191, v201, s[84:85]
	s_add_u32 s84, s46, 0x1a000
	s_addc_u32 s85, s47, 0
	s_nop 1
	global_load_dword v192, v200, s[84:85]
	global_load_dword v193, v201, s[84:85]
	s_add_u32 s84, s46, 0x1c000
	s_addc_u32 s85, s47, 0
	s_nop 1
	global_load_dword v194, v200, s[84:85]
	global_load_dword v195, v201, s[84:85]
	s_add_u32 s84, s46, 0x1e000
	s_addc_u32 s85, s47, 0
	s_nop 1
	global_load_dword v196, v200, s[84:85]
	global_load_dword v197, v201, s[84:85]
	s_waitcnt vmcnt(35)
	v_mul_f32_e32 v3, 0xbfb8aa3b, v162
	v_exp_f32_e32 v3, v3
	s_nop 0
	v_add_f32_e32 v3, 1.0, v3
	v_div_scale_f32 v5, s[86:87], v3, v3, v162
	v_rcp_f32_e32 v7, v5
	v_div_scale_f32 v8, vcc, v162, v3, v162
	v_fma_f32 v9, -v5, v7, 1.0
	v_fmac_f32_e32 v7, v9, v7
	v_mul_f32_e32 v9, v8, v7
	v_fma_f32 v10, -v5, v9, v8
	v_fmac_f32_e32 v9, v10, v7
	v_fma_f32 v5, -v5, v9, v8
	v_div_fmas_f32 v5, v5, v7, v9
	v_div_fixup_f32 v2, v5, v3, v162
	ds_write_b32 v149, v2
	s_waitcnt vmcnt(34)
	v_mul_f32_e32 v3, 0xbfb8aa3b, v163
	v_exp_f32_e32 v3, v3
	s_nop 0
	v_add_f32_e32 v3, 1.0, v3
	v_div_scale_f32 v5, s[86:87], v3, v3, v163
	v_rcp_f32_e32 v7, v5
	v_div_scale_f32 v8, vcc, v163, v3, v163
	v_fma_f32 v9, -v5, v7, 1.0
	v_fmac_f32_e32 v7, v9, v7
	v_mul_f32_e32 v9, v8, v7
	v_fma_f32 v10, -v5, v9, v8
	v_fmac_f32_e32 v9, v10, v7
	v_fma_f32 v5, -v5, v9, v8
	v_div_fmas_f32 v5, v5, v7, v9
	v_div_fixup_f32 v2, v5, v3, v163
	ds_write_b32 v149, v2 offset:2048
	s_waitcnt vmcnt(33)
	v_mul_f32_e32 v3, 0xbfb8aa3b, v164
	v_exp_f32_e32 v3, v3
	s_nop 0
	v_add_f32_e32 v3, 1.0, v3
	v_div_scale_f32 v5, s[86:87], v3, v3, v164
	v_rcp_f32_e32 v7, v5
	v_div_scale_f32 v8, vcc, v164, v3, v164
	v_fma_f32 v9, -v5, v7, 1.0
	v_fmac_f32_e32 v7, v9, v7
	v_mul_f32_e32 v9, v8, v7
	v_fma_f32 v10, -v5, v9, v8
	v_fmac_f32_e32 v9, v10, v7
	v_fma_f32 v5, -v5, v9, v8
	v_div_fmas_f32 v5, v5, v7, v9
	v_div_fixup_f32 v2, v5, v3, v164
	ds_write_b32 v149, v2 offset:4096
	s_waitcnt vmcnt(32)
	v_mul_f32_e32 v3, 0xbfb8aa3b, v165
	v_exp_f32_e32 v3, v3
	s_nop 0
	v_add_f32_e32 v3, 1.0, v3
	v_div_scale_f32 v5, s[86:87], v3, v3, v165
	v_rcp_f32_e32 v7, v5
	v_div_scale_f32 v8, vcc, v165, v3, v165
	v_fma_f32 v9, -v5, v7, 1.0
	v_fmac_f32_e32 v7, v9, v7
	v_mul_f32_e32 v9, v8, v7
	v_fma_f32 v10, -v5, v9, v8
	v_fmac_f32_e32 v9, v10, v7
	v_fma_f32 v5, -v5, v9, v8
	v_div_fmas_f32 v5, v5, v7, v9
	v_div_fixup_f32 v2, v5, v3, v165
	ds_write_b32 v149, v2 offset:6144
	s_waitcnt vmcnt(31)
	v_mul_f32_e32 v3, 0xbfb8aa3b, v166
	v_exp_f32_e32 v3, v3
	s_nop 0
	v_add_f32_e32 v3, 1.0, v3
	v_div_scale_f32 v5, s[86:87], v3, v3, v166
	v_rcp_f32_e32 v7, v5
	v_div_scale_f32 v8, vcc, v166, v3, v166
	v_fma_f32 v9, -v5, v7, 1.0
	v_fmac_f32_e32 v7, v9, v7
	v_mul_f32_e32 v9, v8, v7
	v_fma_f32 v10, -v5, v9, v8
	v_fmac_f32_e32 v9, v10, v7
	v_fma_f32 v5, -v5, v9, v8
	v_div_fmas_f32 v5, v5, v7, v9
	v_div_fixup_f32 v2, v5, v3, v166
	ds_write_b32 v149, v2 offset:8192
	s_waitcnt vmcnt(30)
	v_mul_f32_e32 v3, 0xbfb8aa3b, v167
	v_exp_f32_e32 v3, v3
	s_nop 0
	v_add_f32_e32 v3, 1.0, v3
	v_div_scale_f32 v5, s[86:87], v3, v3, v167
	v_rcp_f32_e32 v7, v5
	v_div_scale_f32 v8, vcc, v167, v3, v167
	v_fma_f32 v9, -v5, v7, 1.0
	v_fmac_f32_e32 v7, v9, v7
	v_mul_f32_e32 v9, v8, v7
	v_fma_f32 v10, -v5, v9, v8
	v_fmac_f32_e32 v9, v10, v7
	v_fma_f32 v5, -v5, v9, v8
	v_div_fmas_f32 v5, v5, v7, v9
	v_div_fixup_f32 v2, v5, v3, v167
	ds_write_b32 v149, v2 offset:10240
	s_waitcnt vmcnt(29)
; __device__ __forceinline__ void adaln_unit(const Args& a, LAS unsigned char* lds, int unit, int tid, int wave, int lane) {
;     ...
;         for (int i = tid; i < 18 * 1024; i += NTHR) { const int r = i >> 10, k = (i & 1023) + kh * 1024; const float c = r < 2 ? a.in[I_CP][r * 2048 + k] : a.in[I_CS][(r - 2) * 2048 + k];
;             sc[i] = c / (1.0f + __expf(-c)); }
	v_mul_f32_e32 v3, 0xbfb8aa3b, v168
	v_exp_f32_e32 v3, v3
	s_nop 0
	v_add_f32_e32 v3, 1.0, v3
	v_div_scale_f32 v5, s[86:87], v3, v3, v168
	v_rcp_f32_e32 v7, v5
	v_div_scale_f32 v8, vcc, v168, v3, v168
	v_fma_f32 v9, -v5, v7, 1.0
	v_fmac_f32_e32 v7, v9, v7
	v_mul_f32_e32 v9, v8, v7
	v_fma_f32 v10, -v5, v9, v8
	v_fmac_f32_e32 v9, v10, v7
	v_fma_f32 v5, -v5, v9, v8
	v_div_fmas_f32 v5, v5, v7, v9
	v_div_fixup_f32 v2, v5, v3, v168
	ds_write_b32 v149, v2 offset:12288
	s_waitcnt vmcnt(28)
	v_mul_f32_e32 v3, 0xbfb8aa3b, v169
	v_exp_f32_e32 v3, v3
	s_nop 0
	v_add_f32_e32 v3, 1.0, v3
	v_div_scale_f32 v5, s[86:87], v3, v3, v169
	v_rcp_f32_e32 v7, v5
	v_div_scale_f32 v8, vcc, v169, v3, v169
	v_fma_f32 v9, -v5, v7, 1.0
	v_fmac_f32_e32 v7, v9, v7
	v_mul_f32_e32 v9, v8, v7
	v_fma_f32 v10, -v5, v9, v8
	v_fmac_f32_e32 v9, v10, v7
	v_fma_f32 v5, -v5, v9, v8
	v_div_fmas_f32 v5, v5, v7, v9
	v_div_fixup_f32 v2, v5, v3, v169
	ds_write_b32 v149, v2 offset:14336
	s_waitcnt vmcnt(27)
	v_mul_f32_e32 v3, 0xbfb8aa3b, v170
	v_exp_f32_e32 v3, v3
	s_nop 0
	v_add_f32_e32 v3, 1.0, v3
	v_div_scale_f32 v5, s[86:87], v3, v3, v170
	v_rcp_f32_e32 v7, v5
	v_div_scale_f32 v8, vcc, v170, v3, v170
	v_fma_f32 v9, -v5, v7, 1.0
	v_fmac_f32_e32 v7, v9, v7
	v_mul_f32_e32 v9, v8, v7
	v_fma_f32 v10, -v5, v9, v8
	v_fmac_f32_e32 v9, v10, v7
	v_fma_f32 v5, -v5, v9, v8
	v_div_fmas_f32 v5, v5, v7, v9
	v_div_fixup_f32 v2, v5, v3, v170
	ds_write_b32 v149, v2 offset:16384
	s_waitcnt vmcnt(26)
	v_mul_f32_e32 v3, 0xbfb8aa3b, v171
	v_exp_f32_e32 v3, v3
	s_nop 0
	v_add_f32_e32 v3, 1.0, v3
	v_div_scale_f32 v5, s[86:87], v3, v3, v171
	v_rcp_f32_e32 v7, v5
	v_div_scale_f32 v8, vcc, v171, v3, v171
	v_fma_f32 v9, -v5, v7, 1.0
	v_fmac_f32_e32 v7, v9, v7
	v_mul_f32_e32 v9, v8, v7
	v_fma_f32 v10, -v5, v9, v8
	v_fmac_f32_e32 v9, v10, v7
	v_fma_f32 v5, -v5, v9, v8
	v_div_fmas_f32 v5, v5, v7, v9
	v_div_fixup_f32 v2, v5, v3, v171
	ds_write_b32 v149, v2 offset:18432
	s_waitcnt vmcnt(25)
	v_mul_f32_e32 v3, 0xbfb8aa3b, v172
	v_exp_f32_e32 v3, v3
	s_nop 0
	v_add_f32_e32 v3, 1.0, v3
	v_div_scale_f32 v5, s[86:87], v3, v3, v172
	v_rcp_f32_e32 v7, v5
	v_div_scale_f32 v8, vcc, v172, v3, v172
	v_fma_f32 v9, -v5, v7, 1.0
	v_fmac_f32_e32 v7, v9, v7
	v_mul_f32_e32 v9, v8, v7
	v_fma_f32 v10, -v5, v9, v8
	v_fmac_f32_e32 v9, v10, v7
	v_fma_f32 v5, -v5, v9, v8
	v_div_fmas_f32 v5, v5, v7, v9
	v_div_fixup_f32 v2, v5, v3, v172
	ds_write_b32 v149, v2 offset:20480
	s_waitcnt vmcnt(24)
	v_mul_f32_e32 v3, 0xbfb8aa3b, v173
	v_exp_f32_e32 v3, v3
	s_nop 0
	v_add_f32_e32 v3, 1.0, v3
	v_div_scale_f32 v5, s[86:87], v3, v3, v173
	v_rcp_f32_e32 v7, v5
	v_div_scale_f32 v8, vcc, v173, v3, v173
	v_fma_f32 v9, -v5, v7, 1.0
	v_fmac_f32_e32 v7, v9, v7
	v_mul_f32_e32 v9, v8, v7
	v_fma_f32 v10, -v5, v9, v8
	v_fmac_f32_e32 v9, v10, v7
	v_fma_f32 v5, -v5, v9, v8
	v_div_fmas_f32 v5, v5, v7, v9
	v_div_fixup_f32 v2, v5, v3, v173
	ds_write_b32 v149, v2 offset:22528
	s_waitcnt vmcnt(23)
	v_mul_f32_e32 v3, 0xbfb8aa3b, v174
	v_exp_f32_e32 v3, v3
	s_nop 0
	v_add_f32_e32 v3, 1.0, v3
	v_div_scale_f32 v5, s[86:87], v3, v3, v174
	v_rcp_f32_e32 v7, v5
	v_div_scale_f32 v8, vcc, v174, v3, v174
	v_fma_f32 v9, -v5, v7, 1.0
	v_fmac_f32_e32 v7, v9, v7
	v_mul_f32_e32 v9, v8, v7
	v_fma_f32 v10, -v5, v9, v8
	v_fmac_f32_e32 v9, v10, v7
	v_fma_f32 v5, -v5, v9, v8
	v_div_fmas_f32 v5, v5, v7, v9
	v_div_fixup_f32 v2, v5, v3, v174
	ds_write_b32 v149, v2 offset:24576
	s_waitcnt vmcnt(22)
	v_mul_f32_e32 v3, 0xbfb8aa3b, v175
	v_exp_f32_e32 v3, v3
	s_nop 0
	v_add_f32_e32 v3, 1.0, v3
	v_div_scale_f32 v5, s[86:87], v3, v3, v175
	v_rcp_f32_e32 v7, v5
	v_div_scale_f32 v8, vcc, v175, v3, v175
	v_fma_f32 v9, -v5, v7, 1.0
	v_fmac_f32_e32 v7, v9, v7
	v_mul_f32_e32 v9, v8, v7
	v_fma_f32 v10, -v5, v9, v8
	v_fmac_f32_e32 v9, v10, v7
	v_fma_f32 v5, -v5, v9, v8
	v_div_fmas_f32 v5, v5, v7, v9
	v_div_fixup_f32 v2, v5, v3, v175
	ds_write_b32 v149, v2 offset:26624
	s_waitcnt vmcnt(21)
	v_mul_f32_e32 v3, 0xbfb8aa3b, v176
	v_exp_f32_e32 v3, v3
	s_nop 0
	v_add_f32_e32 v3, 1.0, v3
	v_div_scale_f32 v5, s[86:87], v3, v3, v176
	v_rcp_f32_e32 v7, v5
	v_div_scale_f32 v8, vcc, v176, v3, v176
	v_fma_f32 v9, -v5, v7, 1.0
	v_fmac_f32_e32 v7, v9, v7
	v_mul_f32_e32 v9, v8, v7
	v_fma_f32 v10, -v5, v9, v8
	v_fmac_f32_e32 v9, v10, v7
	v_fma_f32 v5, -v5, v9, v8
	v_div_fmas_f32 v5, v5, v7, v9
	v_div_fixup_f32 v2, v5, v3, v176
	ds_write_b32 v149, v2 offset:28672
	s_waitcnt vmcnt(20)
	v_mul_f32_e32 v3, 0xbfb8aa3b, v177
	v_exp_f32_e32 v3, v3
	s_nop 0
	v_add_f32_e32 v3, 1.0, v3
	v_div_scale_f32 v5, s[86:87], v3, v3, v177
	v_rcp_f32_e32 v7, v5
	v_div_scale_f32 v8, vcc, v177, v3, v177
	v_fma_f32 v9, -v5, v7, 1.0
	v_fmac_f32_e32 v7, v9, v7
	v_mul_f32_e32 v9, v8, v7
	v_fma_f32 v10, -v5, v9, v8
	v_fmac_f32_e32 v9, v10, v7
	v_fma_f32 v5, -v5, v9, v8
	v_div_fmas_f32 v5, v5, v7, v9
	v_div_fixup_f32 v2, v5, v3, v177
	ds_write_b32 v149, v2 offset:30720
	s_waitcnt vmcnt(19)
	v_mul_f32_e32 v3, 0xbfb8aa3b, v178
	v_exp_f32_e32 v3, v3
	s_nop 0
	v_add_f32_e32 v3, 1.0, v3
	v_div_scale_f32 v5, s[86:87], v3, v3, v178
	v_rcp_f32_e32 v7, v5
	v_div_scale_f32 v8, vcc, v178, v3, v178
	v_fma_f32 v9, -v5, v7, 1.0
	v_fmac_f32_e32 v7, v9, v7
	v_mul_f32_e32 v9, v8, v7
	v_fma_f32 v10, -v5, v9, v8
	v_fmac_f32_e32 v9, v10, v7
	v_fma_f32 v5, -v5, v9, v8
	v_div_fmas_f32 v5, v5, v7, v9
	v_div_fixup_f32 v2, v5, v3, v178
	ds_write_b32 v149, v2 offset:32768
	s_waitcnt vmcnt(18)
	v_mul_f32_e32 v3, 0xbfb8aa3b, v179
	v_exp_f32_e32 v3, v3
	s_nop 0
	v_add_f32_e32 v3, 1.0, v3
	v_div_scale_f32 v5, s[86:87], v3, v3, v179
	v_rcp_f32_e32 v7, v5
	v_div_scale_f32 v8, vcc, v179, v3, v179
	v_fma_f32 v9, -v5, v7, 1.0
	v_fmac_f32_e32 v7, v9, v7
	v_mul_f32_e32 v9, v8, v7
	v_fma_f32 v10, -v5, v9, v8
	v_fmac_f32_e32 v9, v10, v7
	v_fma_f32 v5, -v5, v9, v8
	v_div_fmas_f32 v5, v5, v7, v9
	v_div_fixup_f32 v2, v5, v3, v179
	ds_write_b32 v149, v2 offset:34816
	s_waitcnt vmcnt(17)
; __device__ __forceinline__ void adaln_unit(const Args& a, LAS unsigned char* lds, int unit, int tid, int wave, int lane) {
;     ...
;         for (int i = tid; i < 18 * 1024; i += NTHR) { const int r = i >> 10, k = (i & 1023) + kh * 1024; const float c = r < 2 ? a.in[I_CP][r * 2048 + k] : a.in[I_CS][(r - 2) * 2048 + k];
;             sc[i] = c / (1.0f + __expf(-c)); }
	v_mul_f32_e32 v3, 0xbfb8aa3b, v180
	v_exp_f32_e32 v3, v3
	s_nop 0
	v_add_f32_e32 v3, 1.0, v3
	v_div_scale_f32 v5, s[86:87], v3, v3, v180
	v_rcp_f32_e32 v7, v5
	v_div_scale_f32 v8, vcc, v180, v3, v180
	v_fma_f32 v9, -v5, v7, 1.0
	v_fmac_f32_e32 v7, v9, v7
	v_mul_f32_e32 v9, v8, v7
	v_fma_f32 v10, -v5, v9, v8
	v_fmac_f32_e32 v9, v10, v7
	v_fma_f32 v5, -v5, v9, v8
	v_div_fmas_f32 v5, v5, v7, v9
	v_div_fixup_f32 v2, v5, v3, v180
	ds_write_b32 v149, v2 offset:36864
	s_waitcnt vmcnt(16)
	v_mul_f32_e32 v3, 0xbfb8aa3b, v181
	v_exp_f32_e32 v3, v3
	s_nop 0
	v_add_f32_e32 v3, 1.0, v3
	v_div_scale_f32 v5, s[86:87], v3, v3, v181
	v_rcp_f32_e32 v7, v5
	v_div_scale_f32 v8, vcc, v181, v3, v181
	v_fma_f32 v9, -v5, v7, 1.0
	v_fmac_f32_e32 v7, v9, v7
	v_mul_f32_e32 v9, v8, v7
	v_fma_f32 v10, -v5, v9, v8
	v_fmac_f32_e32 v9, v10, v7
	v_fma_f32 v5, -v5, v9, v8
	v_div_fmas_f32 v5, v5, v7, v9
	v_div_fixup_f32 v2, v5, v3, v181
	ds_write_b32 v149, v2 offset:38912
	s_waitcnt vmcnt(15)
	v_mul_f32_e32 v3, 0xbfb8aa3b, v182
	v_exp_f32_e32 v3, v3
	s_nop 0
	v_add_f32_e32 v3, 1.0, v3
	v_div_scale_f32 v5, s[86:87], v3, v3, v182
	v_rcp_f32_e32 v7, v5
	v_div_scale_f32 v8, vcc, v182, v3, v182
	v_fma_f32 v9, -v5, v7, 1.0
	v_fmac_f32_e32 v7, v9, v7
	v_mul_f32_e32 v9, v8, v7
	v_fma_f32 v10, -v5, v9, v8
	v_fmac_f32_e32 v9, v10, v7
	v_fma_f32 v5, -v5, v9, v8
	v_div_fmas_f32 v5, v5, v7, v9
	v_div_fixup_f32 v2, v5, v3, v182
	ds_write_b32 v149, v2 offset:40960
	s_waitcnt vmcnt(14)
	v_mul_f32_e32 v3, 0xbfb8aa3b, v183
	v_exp_f32_e32 v3, v3
	s_nop 0
	v_add_f32_e32 v3, 1.0, v3
	v_div_scale_f32 v5, s[86:87], v3, v3, v183
	v_rcp_f32_e32 v7, v5
	v_div_scale_f32 v8, vcc, v183, v3, v183
	v_fma_f32 v9, -v5, v7, 1.0
	v_fmac_f32_e32 v7, v9, v7
	v_mul_f32_e32 v9, v8, v7
	v_fma_f32 v10, -v5, v9, v8
	v_fmac_f32_e32 v9, v10, v7
	v_fma_f32 v5, -v5, v9, v8
	v_div_fmas_f32 v5, v5, v7, v9
	v_div_fixup_f32 v2, v5, v3, v183
	ds_write_b32 v149, v2 offset:43008
	s_waitcnt vmcnt(13)
	v_mul_f32_e32 v3, 0xbfb8aa3b, v184
	v_exp_f32_e32 v3, v3
	s_nop 0
	v_add_f32_e32 v3, 1.0, v3
	v_div_scale_f32 v5, s[86:87], v3, v3, v184
	v_rcp_f32_e32 v7, v5
	v_div_scale_f32 v8, vcc, v184, v3, v184
	v_fma_f32 v9, -v5, v7, 1.0
	v_fmac_f32_e32 v7, v9, v7
	v_mul_f32_e32 v9, v8, v7
	v_fma_f32 v10, -v5, v9, v8
	v_fmac_f32_e32 v9, v10, v7
	v_fma_f32 v5, -v5, v9, v8
	v_div_fmas_f32 v5, v5, v7, v9
	v_div_fixup_f32 v2, v5, v3, v184
	ds_write_b32 v149, v2 offset:45056
	s_waitcnt vmcnt(12)
	v_mul_f32_e32 v3, 0xbfb8aa3b, v185
	v_exp_f32_e32 v3, v3
	s_nop 0
	v_add_f32_e32 v3, 1.0, v3
	v_div_scale_f32 v5, s[86:87], v3, v3, v185
	v_rcp_f32_e32 v7, v5
	v_div_scale_f32 v8, vcc, v185, v3, v185
	v_fma_f32 v9, -v5, v7, 1.0
	v_fmac_f32_e32 v7, v9, v7
	v_mul_f32_e32 v9, v8, v7
	v_fma_f32 v10, -v5, v9, v8
	v_fmac_f32_e32 v9, v10, v7
	v_fma_f32 v5, -v5, v9, v8
	v_div_fmas_f32 v5, v5, v7, v9
	v_div_fixup_f32 v2, v5, v3, v185
	ds_write_b32 v149, v2 offset:47104
	s_waitcnt vmcnt(11)
	v_mul_f32_e32 v3, 0xbfb8aa3b, v186
	v_exp_f32_e32 v3, v3
	s_nop 0
	v_add_f32_e32 v3, 1.0, v3
	v_div_scale_f32 v5, s[86:87], v3, v3, v186
	v_rcp_f32_e32 v7, v5
	v_div_scale_f32 v8, vcc, v186, v3, v186
	v_fma_f32 v9, -v5, v7, 1.0
	v_fmac_f32_e32 v7, v9, v7
	v_mul_f32_e32 v9, v8, v7
	v_fma_f32 v10, -v5, v9, v8
	v_fmac_f32_e32 v9, v10, v7
	v_fma_f32 v5, -v5, v9, v8
	v_div_fmas_f32 v5, v5, v7, v9
	v_div_fixup_f32 v2, v5, v3, v186
	ds_write_b32 v149, v2 offset:49152
	s_waitcnt vmcnt(10)
	v_mul_f32_e32 v3, 0xbfb8aa3b, v187
	v_exp_f32_e32 v3, v3
	s_nop 0
	v_add_f32_e32 v3, 1.0, v3
	v_div_scale_f32 v5, s[86:87], v3, v3, v187
	v_rcp_f32_e32 v7, v5
	v_div_scale_f32 v8, vcc, v187, v3, v187
	v_fma_f32 v9, -v5, v7, 1.0
	v_fmac_f32_e32 v7, v9, v7
	v_mul_f32_e32 v9, v8, v7
	v_fma_f32 v10, -v5, v9, v8
	v_fmac_f32_e32 v9, v10, v7
	v_fma_f32 v5, -v5, v9, v8
	v_div_fmas_f32 v5, v5, v7, v9
	v_div_fixup_f32 v2, v5, v3, v187
	ds_write_b32 v149, v2 offset:51200
	s_waitcnt vmcnt(9)
	v_mul_f32_e32 v3, 0xbfb8aa3b, v188
	v_exp_f32_e32 v3, v3
	s_nop 0
	v_add_f32_e32 v3, 1.0, v3
	v_div_scale_f32 v5, s[86:87], v3, v3, v188
	v_rcp_f32_e32 v7, v5
	v_div_scale_f32 v8, vcc, v188, v3, v188
	v_fma_f32 v9, -v5, v7, 1.0
	v_fmac_f32_e32 v7, v9, v7
	v_mul_f32_e32 v9, v8, v7
	v_fma_f32 v10, -v5, v9, v8
	v_fmac_f32_e32 v9, v10, v7
	v_fma_f32 v5, -v5, v9, v8
	v_div_fmas_f32 v5, v5, v7, v9
	v_div_fixup_f32 v2, v5, v3, v188
	ds_write_b32 v149, v2 offset:53248
	s_waitcnt vmcnt(8)
; __device__ __forceinline__ void adaln_unit(const Args& a, LAS unsigned char* lds, int unit, int tid, int wave, int lane) {
;     ...
;         for (int i = tid; i < 18 * 1024; i += NTHR) { const int r = i >> 10, k = (i & 1023) + kh * 1024; const float c = r < 2 ? a.in[I_CP][r * 2048 + k] : a.in[I_CS][(r - 2) * 2048 + k];
;             sc[i] = c / (1.0f + __expf(-c)); }
	v_mul_f32_e32 v3, 0xbfb8aa3b, v189
	v_exp_f32_e32 v3, v3
	s_nop 0
	v_add_f32_e32 v3, 1.0, v3
	v_div_scale_f32 v5, s[86:87], v3, v3, v189
	v_rcp_f32_e32 v7, v5
	v_div_scale_f32 v8, vcc, v189, v3, v189
	v_fma_f32 v9, -v5, v7, 1.0
	v_fmac_f32_e32 v7, v9, v7
	v_mul_f32_e32 v9, v8, v7
	v_fma_f32 v10, -v5, v9, v8
	v_fmac_f32_e32 v9, v10, v7
	v_fma_f32 v5, -v5, v9, v8
	v_div_fmas_f32 v5, v5, v7, v9
	v_div_fixup_f32 v2, v5, v3, v189
	ds_write_b32 v149, v2 offset:55296
	s_waitcnt vmcnt(7)
	v_mul_f32_e32 v3, 0xbfb8aa3b, v190
	v_exp_f32_e32 v3, v3
	s_nop 0
	v_add_f32_e32 v3, 1.0, v3
	v_div_scale_f32 v5, s[86:87], v3, v3, v190
	v_rcp_f32_e32 v7, v5
	v_div_scale_f32 v8, vcc, v190, v3, v190
	v_fma_f32 v9, -v5, v7, 1.0
	v_fmac_f32_e32 v7, v9, v7
	v_mul_f32_e32 v9, v8, v7
	v_fma_f32 v10, -v5, v9, v8
	v_fmac_f32_e32 v9, v10, v7
	v_fma_f32 v5, -v5, v9, v8
	v_div_fmas_f32 v5, v5, v7, v9
	v_div_fixup_f32 v2, v5, v3, v190
	ds_write_b32 v149, v2 offset:57344
	s_waitcnt vmcnt(6)
	v_mul_f32_e32 v3, 0xbfb8aa3b, v191
	v_exp_f32_e32 v3, v3
	s_nop 0
	v_add_f32_e32 v3, 1.0, v3
	v_div_scale_f32 v5, s[86:87], v3, v3, v191
	v_rcp_f32_e32 v7, v5
	v_div_scale_f32 v8, vcc, v191, v3, v191
	v_fma_f32 v9, -v5, v7, 1.0
	v_fmac_f32_e32 v7, v9, v7
	v_mul_f32_e32 v9, v8, v7
	v_fma_f32 v10, -v5, v9, v8
	v_fmac_f32_e32 v9, v10, v7
	v_fma_f32 v5, -v5, v9, v8
	v_div_fmas_f32 v5, v5, v7, v9
	v_div_fixup_f32 v2, v5, v3, v191
	ds_write_b32 v149, v2 offset:59392
	s_waitcnt vmcnt(5)
	v_mul_f32_e32 v3, 0xbfb8aa3b, v192
	v_exp_f32_e32 v3, v3
	s_nop 0
	v_add_f32_e32 v3, 1.0, v3
	v_div_scale_f32 v5, s[86:87], v3, v3, v192
	v_rcp_f32_e32 v7, v5
	v_div_scale_f32 v8, vcc, v192, v3, v192
	v_fma_f32 v9, -v5, v7, 1.0
	v_fmac_f32_e32 v7, v9, v7
	v_mul_f32_e32 v9, v8, v7
	v_fma_f32 v10, -v5, v9, v8
	v_fmac_f32_e32 v9, v10, v7
	v_fma_f32 v5, -v5, v9, v8
	v_div_fmas_f32 v5, v5, v7, v9
	v_div_fixup_f32 v2, v5, v3, v192
	ds_write_b32 v149, v2 offset:61440
	s_waitcnt vmcnt(4)
	v_mul_f32_e32 v3, 0xbfb8aa3b, v193
	v_exp_f32_e32 v3, v3
	s_nop 0
	v_add_f32_e32 v3, 1.0, v3
	v_div_scale_f32 v5, s[86:87], v3, v3, v193
	v_rcp_f32_e32 v7, v5
	v_div_scale_f32 v8, vcc, v193, v3, v193
	v_fma_f32 v9, -v5, v7, 1.0
	v_fmac_f32_e32 v7, v9, v7
	v_mul_f32_e32 v9, v8, v7
	v_fma_f32 v10, -v5, v9, v8
	v_fmac_f32_e32 v9, v10, v7
	v_fma_f32 v5, -v5, v9, v8
	v_div_fmas_f32 v5, v5, v7, v9
	v_div_fixup_f32 v2, v5, v3, v193
	ds_write_b32 v149, v2 offset:63488
	s_waitcnt vmcnt(3)
	v_mul_f32_e32 v3, 0xbfb8aa3b, v194
	v_exp_f32_e32 v3, v3
	s_nop 0
	v_add_f32_e32 v3, 1.0, v3
	v_div_scale_f32 v5, s[86:87], v3, v3, v194
	v_rcp_f32_e32 v7, v5
	v_div_scale_f32 v8, vcc, v194, v3, v194
	v_fma_f32 v9, -v5, v7, 1.0
	v_fmac_f32_e32 v7, v9, v7
	v_mul_f32_e32 v9, v8, v7
	v_fma_f32 v10, -v5, v9, v8
	v_fmac_f32_e32 v9, v10, v7
	v_fma_f32 v5, -v5, v9, v8
	v_div_fmas_f32 v5, v5, v7, v9
	v_div_fixup_f32 v2, v5, v3, v194
	ds_write_b32 v202, v2
	s_waitcnt vmcnt(2)
	v_mul_f32_e32 v3, 0xbfb8aa3b, v195
	v_exp_f32_e32 v3, v3
	s_nop 0
	v_add_f32_e32 v3, 1.0, v3
	v_div_scale_f32 v5, s[86:87], v3, v3, v195
	v_rcp_f32_e32 v7, v5
	v_div_scale_f32 v8, vcc, v195, v3, v195
	v_fma_f32 v9, -v5, v7, 1.0
	v_fmac_f32_e32 v7, v9, v7
	v_mul_f32_e32 v9, v8, v7
	v_fma_f32 v10, -v5, v9, v8
	v_fmac_f32_e32 v9, v10, v7
	v_fma_f32 v5, -v5, v9, v8
	v_div_fmas_f32 v5, v5, v7, v9
	v_div_fixup_f32 v2, v5, v3, v195
	ds_write_b32 v202, v2 offset:2048
	s_waitcnt vmcnt(1)
	v_mul_f32_e32 v3, 0xbfb8aa3b, v196
	v_exp_f32_e32 v3, v3
	s_nop 0
	v_add_f32_e32 v3, 1.0, v3
	v_div_scale_f32 v5, s[86:87], v3, v3, v196
	v_rcp_f32_e32 v7, v5
	v_div_scale_f32 v8, vcc, v196, v3, v196
	v_fma_f32 v9, -v5, v7, 1.0
	v_fmac_f32_e32 v7, v9, v7
	v_mul_f32_e32 v9, v8, v7
	v_fma_f32 v10, -v5, v9, v8
	v_fmac_f32_e32 v9, v10, v7
	v_fma_f32 v5, -v5, v9, v8
	v_div_fmas_f32 v5, v5, v7, v9
	v_div_fixup_f32 v2, v5, v3, v196
	ds_write_b32 v202, v2 offset:4096
	s_waitcnt vmcnt(0)
	v_mul_f32_e32 v3, 0xbfb8aa3b, v197
	v_exp_f32_e32 v3, v3
	s_nop 0
	v_add_f32_e32 v3, 1.0, v3
	v_div_scale_f32 v5, s[86:87], v3, v3, v197
	v_rcp_f32_e32 v7, v5
	v_div_scale_f32 v8, vcc, v197, v3, v197
	v_fma_f32 v9, -v5, v7, 1.0
	v_fmac_f32_e32 v7, v9, v7
	v_mul_f32_e32 v9, v8, v7
	v_fma_f32 v10, -v5, v9, v8
	v_fmac_f32_e32 v9, v10, v7
	v_fma_f32 v5, -v5, v9, v8
	v_div_fmas_f32 v5, v5, v7, v9
	v_div_fixup_f32 v2, v5, v3, v197
	ds_write_b32 v202, v2 offset:6144
